# grid-barrier spin loops poll back-to-back (the 100 s_sleep 1 removed)
# speedup vs baseline: 1.0025x; 1.0025x over previous
.LBB0_74:
	global_load_dword v2, v0, s[4:5] offset:32 sc1
	s_waitcnt vmcnt(0)
	v_and_b32_e32 v2, 0xffff0000, v2
	v_cmp_ne_u32_e32 vcc, v2, v1
	s_or_b64 s[6:7], vcc, s[6:7]
	s_andn2_b64 exec, exec, s[6:7]
	s_cbranch_execnz .LBB0_74

.LBB0_87:
	global_load_dword v15, v16, s[6:7] sc1
	s_waitcnt lgkmcnt(0)
	global_load_dword v0, v16, s[10:11] sc1
	global_load_dword v1, v16, s[12:13] sc1
	global_load_dword v2, v16, s[16:17] sc1
	global_load_dword v3, v16, s[18:19] sc1
	global_load_dword v4, v16, s[20:21] sc1
	global_load_dword v5, v16, s[22:23] sc1
	global_load_dword v6, v16, s[24:25] sc1
	global_load_dword v7, v16, s[26:27] sc1
	global_load_dword v8, v16, s[28:29] sc1
	global_load_dword v9, v16, s[30:31] sc1
	global_load_dword v10, v16, s[34:35] sc1
	global_load_dword v11, v16, s[36:37] sc1
	global_load_dword v12, v16, s[62:63] sc1
	global_load_dword v13, v16, s[64:65] sc1
	global_load_dword v14, v16, s[66:67] sc1
	s_mov_b64 s[72:73], -1
	s_mov_b64 s[74:75], -1
	s_waitcnt vmcnt(14)
	v_add_u32_e32 v17, v0, v15
	s_waitcnt vmcnt(13)
	v_add_u32_e32 v17, v17, v1
	s_waitcnt vmcnt(12)
	v_add_u32_e32 v17, v17, v2
	s_waitcnt vmcnt(11)
	v_add_u32_e32 v17, v17, v3
	s_waitcnt vmcnt(10)
	v_add_u32_e32 v17, v17, v4
	s_waitcnt vmcnt(9)
	v_add_u32_e32 v17, v17, v5
	s_waitcnt vmcnt(8)
	v_add_u32_e32 v17, v17, v6
	s_waitcnt vmcnt(7)
	v_add_u32_e32 v17, v17, v7
	s_waitcnt vmcnt(6)
	v_add_u32_e32 v17, v17, v8
	s_waitcnt vmcnt(5)
	v_add_u32_e32 v17, v17, v9
	s_waitcnt vmcnt(4)
	v_add_u32_e32 v17, v17, v10
	s_waitcnt vmcnt(3)
	v_add_u32_e32 v17, v17, v11
	s_waitcnt vmcnt(2)
	v_add_u32_e32 v17, v17, v12
	s_waitcnt vmcnt(1)
	v_add_u32_e32 v17, v17, v13
	s_waitcnt vmcnt(0)
	v_add_u32_e32 v17, v17, v14
	v_cmp_eq_u32_e32 vcc, s2, v17
	s_cbranch_vccnz .LBB0_86
	s_and_b32 s15, s14, 0xff
	s_cmp_eq_u32 s15, 0
	s_mov_b64 s[78:79], -1
	s_cbranch_scc1 .LBB0_91
	s_and_b64 vcc, exec, s[78:79]
	s_cbranch_vccz .LBB0_86

.LBB0_105:
	s_and_b32 s14, s2, 0xff
	s_mov_b64 s[22:23], -1
	s_cmp_lg_u32 s14, 0
	s_mov_b64 s[26:27], -1
	s_cbranch_scc0 .LBB0_108
	s_and_b64 vcc, exec, s[26:27]
	s_cbranch_vccz .LBB0_104

.LBB0_122:
	s_and_b32 s14, s2, 0xff
	s_cmp_lg_u32 s14, 0
	s_mov_b64 s[24:25], -1
	s_cbranch_scc0 .LBB0_125
	s_mov_b64 s[26:27], -1
	s_and_b64 vcc, exec, s[24:25]
	s_cbranch_vccz .LBB0_121

.LBB0_397:
	global_load_dword v15, v16, s[8:9] sc1
	s_waitcnt lgkmcnt(0)
	global_load_dword v0, v16, s[10:11] sc1
	global_load_dword v1, v16, s[12:13] sc1
	global_load_dword v2, v16, s[14:15] sc1
	global_load_dword v3, v16, s[16:17] sc1
	global_load_dword v4, v16, s[18:19] sc1
	global_load_dword v5, v16, s[20:21] sc1
	global_load_dword v6, v16, s[22:23] sc1
	global_load_dword v7, v16, s[24:25] sc1
	global_load_dword v8, v16, s[26:27] sc1
	global_load_dword v9, v16, s[28:29] sc1
	global_load_dword v10, v16, s[30:31] sc1
	global_load_dword v11, v16, s[34:35] sc1
	global_load_dword v12, v16, s[36:37] sc1
	global_load_dword v13, v16, s[62:63] sc1
	global_load_dword v14, v16, s[64:65] sc1
	s_mov_b64 s[66:67], -1
	s_mov_b64 s[72:73], -1
	s_waitcnt vmcnt(14)
	v_add_u32_e32 v17, v0, v15
	s_waitcnt vmcnt(13)
	v_add_u32_e32 v17, v17, v1
	s_waitcnt vmcnt(12)
	v_add_u32_e32 v17, v17, v2
	s_waitcnt vmcnt(11)
	v_add_u32_e32 v17, v17, v3
	s_waitcnt vmcnt(10)
	v_add_u32_e32 v17, v17, v4
	s_waitcnt vmcnt(9)
	v_add_u32_e32 v17, v17, v5
	s_waitcnt vmcnt(8)
	v_add_u32_e32 v17, v17, v6
	s_waitcnt vmcnt(7)
	v_add_u32_e32 v17, v17, v7
	s_waitcnt vmcnt(6)
	v_add_u32_e32 v17, v17, v8
	s_waitcnt vmcnt(5)
	v_add_u32_e32 v17, v17, v9
	s_waitcnt vmcnt(4)
	v_add_u32_e32 v17, v17, v10
	s_waitcnt vmcnt(3)
	v_add_u32_e32 v17, v17, v11
	s_waitcnt vmcnt(2)
	v_add_u32_e32 v17, v17, v12
	s_waitcnt vmcnt(1)
	v_add_u32_e32 v17, v17, v13
	s_waitcnt vmcnt(0)
	v_add_u32_e32 v17, v17, v14
	v_cmp_eq_u32_e32 vcc, s2, v17
	s_cbranch_vccnz .LBB0_396
	s_and_b32 s38, s33, 0xff
	s_cmp_eq_u32 s38, 0
	s_mov_b64 s[74:75], -1
	s_cbranch_scc1 .LBB0_401
	s_and_b64 vcc, exec, s[74:75]
	s_cbranch_vccz .LBB0_396

.LBB0_415:
	s_and_b32 s22, s2, 0xff
	s_mov_b64 s[20:21], -1
	s_cmp_lg_u32 s22, 0
	s_mov_b64 s[24:25], -1
	s_cbranch_scc0 .LBB0_418
	s_and_b64 vcc, exec, s[24:25]
	s_cbranch_vccz .LBB0_414

.LBB0_432:
	s_and_b32 s20, s2, 0xff
	s_cmp_lg_u32 s20, 0
	s_mov_b64 s[22:23], -1
	s_cbranch_scc0 .LBB0_435
	s_mov_b64 s[24:25], -1
	s_and_b64 vcc, exec, s[22:23]
	s_cbranch_vccz .LBB0_431

.LBB0_519:
	global_load_dword v15, v16, s[6:7] sc1
	s_waitcnt lgkmcnt(0)
	global_load_dword v0, v16, s[8:9] sc1
	global_load_dword v1, v16, s[10:11] sc1
	global_load_dword v2, v16, s[12:13] sc1
	global_load_dword v3, v16, s[14:15] sc1
	global_load_dword v4, v16, s[16:17] sc1
	global_load_dword v5, v16, s[18:19] sc1
	global_load_dword v6, v16, s[20:21] sc1
	global_load_dword v7, v16, s[22:23] sc1
	global_load_dword v8, v16, s[24:25] sc1
	global_load_dword v9, v16, s[26:27] sc1
	global_load_dword v10, v16, s[28:29] sc1
	global_load_dword v11, v16, s[30:31] sc1
	global_load_dword v12, v16, s[34:35] sc1
	global_load_dword v13, v16, s[36:37] sc1
	global_load_dword v14, v16, s[64:65] sc1
	s_mov_b64 s[66:67], -1
	s_mov_b64 s[72:73], -1
	s_waitcnt vmcnt(14)
	v_add_u32_e32 v17, v0, v15
	s_waitcnt vmcnt(13)
	v_add_u32_e32 v17, v17, v1
	s_waitcnt vmcnt(12)
	v_add_u32_e32 v17, v17, v2
	s_waitcnt vmcnt(11)
	v_add_u32_e32 v17, v17, v3
	s_waitcnt vmcnt(10)
	v_add_u32_e32 v17, v17, v4
	s_waitcnt vmcnt(9)
	v_add_u32_e32 v17, v17, v5
	s_waitcnt vmcnt(8)
	v_add_u32_e32 v17, v17, v6
	s_waitcnt vmcnt(7)
	v_add_u32_e32 v17, v17, v7
	s_waitcnt vmcnt(6)
	v_add_u32_e32 v17, v17, v8
	s_waitcnt vmcnt(5)
	v_add_u32_e32 v17, v17, v9
	s_waitcnt vmcnt(4)
	v_add_u32_e32 v17, v17, v10
	s_waitcnt vmcnt(3)
	v_add_u32_e32 v17, v17, v11
	s_waitcnt vmcnt(2)
	v_add_u32_e32 v17, v17, v12
	s_waitcnt vmcnt(1)
	v_add_u32_e32 v17, v17, v13
	s_waitcnt vmcnt(0)
	v_add_u32_e32 v17, v17, v14
	v_cmp_eq_u32_e32 vcc, s2, v17
	s_cbranch_vccnz .LBB0_518
	s_and_b32 s38, s33, 0xff
	s_cmp_eq_u32 s38, 0
	s_mov_b64 s[74:75], -1
	s_cbranch_scc1 .LBB0_523
	s_and_b64 vcc, exec, s[74:75]
	s_cbranch_vccz .LBB0_518

.LBB0_537:
	s_and_b32 s20, s2, 0xff
	s_mov_b64 s[18:19], -1
	s_cmp_lg_u32 s20, 0
	s_mov_b64 s[22:23], -1
	s_cbranch_scc0 .LBB0_540
	s_and_b64 vcc, exec, s[22:23]
	s_cbranch_vccz .LBB0_536

.LBB0_554:
	s_and_b32 s18, s2, 0xff
	s_cmp_lg_u32 s18, 0
	s_mov_b64 s[20:21], -1
	s_cbranch_scc0 .LBB0_557
	s_mov_b64 s[22:23], -1
	s_and_b64 vcc, exec, s[20:21]
	s_cbranch_vccz .LBB0_553

.LBB0_791:
	global_load_dword v15, v16, s[8:9] sc1
	s_waitcnt lgkmcnt(0)
	global_load_dword v0, v16, s[10:11] sc1
	global_load_dword v1, v16, s[12:13] sc1
	global_load_dword v2, v16, s[14:15] sc1
	global_load_dword v3, v16, s[16:17] sc1
	global_load_dword v4, v16, s[18:19] sc1
	global_load_dword v5, v16, s[20:21] sc1
	global_load_dword v6, v16, s[22:23] sc1
	global_load_dword v7, v16, s[24:25] sc1
	global_load_dword v8, v16, s[26:27] sc1
	global_load_dword v9, v16, s[28:29] sc1
	global_load_dword v10, v16, s[30:31] sc1
	global_load_dword v11, v16, s[34:35] sc1
	global_load_dword v12, v16, s[36:37] sc1
	global_load_dword v13, v16, s[64:65] sc1
	global_load_dword v14, v16, s[72:73] sc1
	s_mov_b64 s[74:75], -1
	s_mov_b64 s[78:79], -1
	s_waitcnt vmcnt(14)
	v_add_u32_e32 v17, v0, v15
	s_waitcnt vmcnt(13)
	v_add_u32_e32 v17, v17, v1
	s_waitcnt vmcnt(12)
	v_add_u32_e32 v17, v17, v2
	s_waitcnt vmcnt(11)
	v_add_u32_e32 v17, v17, v3
	s_waitcnt vmcnt(10)
	v_add_u32_e32 v17, v17, v4
	s_waitcnt vmcnt(9)
	v_add_u32_e32 v17, v17, v5
	s_waitcnt vmcnt(8)
	v_add_u32_e32 v17, v17, v6
	s_waitcnt vmcnt(7)
	v_add_u32_e32 v17, v17, v7
	s_waitcnt vmcnt(6)
	v_add_u32_e32 v17, v17, v8
	s_waitcnt vmcnt(5)
	v_add_u32_e32 v17, v17, v9
	s_waitcnt vmcnt(4)
	v_add_u32_e32 v17, v17, v10
	s_waitcnt vmcnt(3)
	v_add_u32_e32 v17, v17, v11
	s_waitcnt vmcnt(2)
	v_add_u32_e32 v17, v17, v12
	s_waitcnt vmcnt(1)
	v_add_u32_e32 v17, v17, v13
	s_waitcnt vmcnt(0)
	v_add_u32_e32 v17, v17, v14
	v_cmp_eq_u32_e32 vcc, s2, v17
	s_cbranch_vccnz .LBB0_790
	s_and_b32 s4, s33, 0xff
	s_cmp_eq_u32 s4, 0
	s_mov_b64 s[4:5], -1
	s_cbranch_scc1 .LBB0_795
	s_and_b64 vcc, exec, s[4:5]
	s_cbranch_vccz .LBB0_790

.LBB0_809:
	s_and_b32 s20, s2, 0xff
	s_mov_b64 s[4:5], -1
	s_cmp_lg_u32 s20, 0
	s_mov_b64 s[22:23], -1
	s_cbranch_scc0 .LBB0_812
	s_and_b64 vcc, exec, s[22:23]
	s_cbranch_vccz .LBB0_808

.LBB0_826:
	s_and_b32 s4, s2, 0xff
	s_cmp_lg_u32 s4, 0
	s_mov_b64 s[20:21], -1
	s_cbranch_scc0 .LBB0_829
	s_mov_b64 s[22:23], -1
	s_and_b64 vcc, exec, s[20:21]
	s_cbranch_vccz .LBB0_825

.LBB0_886:
	global_load_dword v15, v16, s[10:11] sc1
	s_waitcnt lgkmcnt(0)
	global_load_dword v0, v16, s[12:13] sc1
	global_load_dword v1, v16, s[14:15] sc1
	global_load_dword v2, v16, s[16:17] sc1
	global_load_dword v3, v16, s[18:19] sc1
	global_load_dword v4, v16, s[20:21] sc1
	global_load_dword v5, v16, s[22:23] sc1
	global_load_dword v6, v16, s[24:25] sc1
	global_load_dword v7, v16, s[26:27] sc1
	global_load_dword v8, v16, s[28:29] sc1
	global_load_dword v9, v16, s[30:31] sc1
	global_load_dword v10, v16, s[34:35] sc1
	global_load_dword v11, v16, s[36:37] sc1
	global_load_dword v12, v16, s[56:57] sc1
	global_load_dword v13, v16, s[60:61] sc1
	global_load_dword v14, v16, s[64:65] sc1
	s_mov_b64 s[72:73], -1
	s_mov_b64 s[74:75], -1
	s_waitcnt vmcnt(14)
	v_add_u32_e32 v17, v0, v15
	s_waitcnt vmcnt(13)
	v_add_u32_e32 v17, v17, v1
	s_waitcnt vmcnt(12)
	v_add_u32_e32 v17, v17, v2
	s_waitcnt vmcnt(11)
	v_add_u32_e32 v17, v17, v3
	s_waitcnt vmcnt(10)
	v_add_u32_e32 v17, v17, v4
	s_waitcnt vmcnt(9)
	v_add_u32_e32 v17, v17, v5
	s_waitcnt vmcnt(8)
	v_add_u32_e32 v17, v17, v6
	s_waitcnt vmcnt(7)
	v_add_u32_e32 v17, v17, v7
	s_waitcnt vmcnt(6)
	v_add_u32_e32 v17, v17, v8
	s_waitcnt vmcnt(5)
	v_add_u32_e32 v17, v17, v9
	s_waitcnt vmcnt(4)
	v_add_u32_e32 v17, v17, v10
	s_waitcnt vmcnt(3)
	v_add_u32_e32 v17, v17, v11
	s_waitcnt vmcnt(2)
	v_add_u32_e32 v17, v17, v12
	s_waitcnt vmcnt(1)
	v_add_u32_e32 v17, v17, v13
	s_waitcnt vmcnt(0)
	v_add_u32_e32 v17, v17, v14
	v_cmp_eq_u32_e32 vcc, s2, v17
	s_cbranch_vccnz .LBB0_885
	s_and_b32 s4, s6, 0xff
	s_cmp_eq_u32 s4, 0
	s_mov_b64 s[4:5], -1
	s_cbranch_scc1 .LBB0_890
	s_and_b64 vcc, exec, s[4:5]
	s_cbranch_vccz .LBB0_885

.LBB0_904:
	s_and_b32 s6, s2, 0xff
	s_mov_b64 s[4:5], -1
	s_cmp_lg_u32 s6, 0
	s_mov_b64 s[24:25], -1
	s_cbranch_scc0 .LBB0_907
	s_and_b64 vcc, exec, s[24:25]
	s_cbranch_vccz .LBB0_903

.LBB0_921:
	s_and_b32 s4, s2, 0xff
	s_cmp_lg_u32 s4, 0
	s_mov_b64 s[22:23], -1
	s_cbranch_scc0 .LBB0_924
	s_mov_b64 s[24:25], -1
	s_and_b64 vcc, exec, s[22:23]
	s_cbranch_vccz .LBB0_920

.LBB0_1039:
	global_load_dword v15, v16, s[10:11] sc1
	s_waitcnt lgkmcnt(0)
	global_load_dword v0, v16, s[12:13] sc1
	global_load_dword v1, v16, s[14:15] sc1
	global_load_dword v2, v16, s[24:25] sc1
	global_load_dword v3, v16, s[26:27] sc1
	global_load_dword v4, v16, s[40:41] sc1
	global_load_dword v5, v16, s[42:43] sc1
	global_load_dword v6, v16, s[44:45] sc1
	global_load_dword v7, v16, s[46:47] sc1
	global_load_dword v8, v16, s[48:49] sc1
	global_load_dword v9, v16, s[50:51] sc1
	global_load_dword v10, v16, s[56:57] sc1
	global_load_dword v11, v16, s[64:65] sc1
	global_load_dword v12, v16, s[72:73] sc1
	global_load_dword v13, v16, s[74:75] sc1
	global_load_dword v14, v16, s[84:85] sc1
	s_mov_b64 s[86:87], -1
	s_mov_b64 s[90:91], -1
	s_waitcnt vmcnt(14)
	v_add_u32_e32 v17, v0, v15
	s_waitcnt vmcnt(13)
	v_add_u32_e32 v17, v17, v1
	s_waitcnt vmcnt(12)
	v_add_u32_e32 v17, v17, v2
	s_waitcnt vmcnt(11)
	v_add_u32_e32 v17, v17, v3
	s_waitcnt vmcnt(10)
	v_add_u32_e32 v17, v17, v4
	s_waitcnt vmcnt(9)
	v_add_u32_e32 v17, v17, v5
	s_waitcnt vmcnt(8)
	v_add_u32_e32 v17, v17, v6
	s_waitcnt vmcnt(7)
	v_add_u32_e32 v17, v17, v7
	s_waitcnt vmcnt(6)
	v_add_u32_e32 v17, v17, v8
	s_waitcnt vmcnt(5)
	v_add_u32_e32 v17, v17, v9
	s_waitcnt vmcnt(4)
	v_add_u32_e32 v17, v17, v10
	s_waitcnt vmcnt(3)
	v_add_u32_e32 v17, v17, v11
	s_waitcnt vmcnt(2)
	v_add_u32_e32 v17, v17, v12
	s_waitcnt vmcnt(1)
	v_add_u32_e32 v17, v17, v13
	s_waitcnt vmcnt(0)
	v_add_u32_e32 v17, v17, v14
	v_cmp_eq_u32_e32 vcc, s2, v17
	s_cbranch_vccnz .LBB0_1038
	s_and_b32 s4, s6, 0xff
	s_cmp_eq_u32 s4, 0
	s_mov_b64 s[4:5], -1
	s_cbranch_scc1 .LBB0_1043
	s_and_b64 vcc, exec, s[4:5]
	s_cbranch_vccz .LBB0_1038

.LBB0_1057:
	s_and_b32 s6, s2, 0xff
	s_mov_b64 s[4:5], -1
	s_cmp_lg_u32 s6, 0
	s_mov_b64 s[44:45], -1
	s_cbranch_scc0 .LBB0_1060
	s_and_b64 vcc, exec, s[44:45]
	s_cbranch_vccz .LBB0_1056

.LBB0_1074:
	s_and_b32 s4, s2, 0xff
	s_cmp_lg_u32 s4, 0
	s_mov_b64 s[42:43], -1
	s_cbranch_scc0 .LBB0_1077
	s_mov_b64 s[44:45], -1
	s_and_b64 vcc, exec, s[42:43]
	s_cbranch_vccz .LBB0_1073

.LBB0_1107:
	global_load_dword v15, v16, s[10:11] sc1
	global_load_dword v0, v16, s[12:13] sc1
	global_load_dword v1, v16, s[14:15] sc1
	global_load_dword v2, v16, s[24:25] sc1
	global_load_dword v3, v16, s[26:27] sc1
	global_load_dword v4, v16, s[42:43] sc1
	global_load_dword v5, v16, s[44:45] sc1
	global_load_dword v6, v16, s[46:47] sc1
	global_load_dword v7, v16, s[48:49] sc1
	global_load_dword v8, v16, s[50:51] sc1
	global_load_dword v9, v16, s[54:55] sc1
	global_load_dword v10, v16, s[64:65] sc1
	global_load_dword v11, v16, s[72:73] sc1
	global_load_dword v12, v16, s[74:75] sc1
	global_load_dword v13, v16, s[84:85] sc1
	global_load_dword v14, v16, s[86:87] sc1
	s_mov_b64 s[90:91], -1
	s_mov_b64 s[40:41], -1
	s_waitcnt vmcnt(14)
	v_add_u32_e32 v17, v0, v15
	s_waitcnt vmcnt(13)
	v_add_u32_e32 v17, v17, v1
	s_waitcnt vmcnt(12)
	v_add_u32_e32 v17, v17, v2
	s_waitcnt vmcnt(11)
	v_add_u32_e32 v17, v17, v3
	s_waitcnt vmcnt(10)
	v_add_u32_e32 v17, v17, v4
	s_waitcnt vmcnt(9)
	v_add_u32_e32 v17, v17, v5
	s_waitcnt vmcnt(8)
	v_add_u32_e32 v17, v17, v6
	s_waitcnt vmcnt(7)
	v_add_u32_e32 v17, v17, v7
	s_waitcnt vmcnt(6)
	v_add_u32_e32 v17, v17, v8
	s_waitcnt vmcnt(5)
	v_add_u32_e32 v17, v17, v9
	s_waitcnt vmcnt(4)
	v_add_u32_e32 v17, v17, v10
	s_waitcnt vmcnt(3)
	v_add_u32_e32 v17, v17, v11
	s_waitcnt vmcnt(2)
	v_add_u32_e32 v17, v17, v12
	s_waitcnt vmcnt(1)
	v_add_u32_e32 v17, v17, v13
	s_waitcnt vmcnt(0)
	v_add_u32_e32 v17, v17, v14
	v_cmp_eq_u32_e32 vcc, s6, v17
	s_cbranch_vccnz .LBB0_1106
	s_and_b32 s4, s2, 0xff
	s_cmp_eq_u32 s4, 0
	s_mov_b64 s[4:5], -1
	s_cbranch_scc1 .LBB0_1111
	s_and_b64 vcc, exec, s[4:5]
	s_cbranch_vccz .LBB0_1106

.LBB0_1142:
	s_and_b32 s4, s2, 0xff
	s_cmp_lg_u32 s4, 0
	s_mov_b64 s[40:41], -1
	s_cbranch_scc0 .LBB0_1145
	s_mov_b64 s[44:45], -1
	s_and_b64 vcc, exec, s[40:41]
	s_cbranch_vccz .LBB0_1141

.LBB0_1206:
	global_load_dword v15, v16, s[10:11] sc1
	global_load_dword v0, v16, s[12:13] sc1
	global_load_dword v1, v16, s[14:15] sc1
	global_load_dword v2, v16, s[24:25] sc1
	global_load_dword v3, v16, s[26:27] sc1
	global_load_dword v4, v16, s[38:39] sc1
	global_load_dword v5, v16, s[42:43] sc1
	global_load_dword v6, v16, s[44:45] sc1
	global_load_dword v7, v16, s[46:47] sc1
	global_load_dword v8, v16, s[48:49] sc1
	global_load_dword v9, v16, s[50:51] sc1
	global_load_dword v10, v16, s[54:55] sc1
	global_load_dword v11, v16, s[64:65] sc1
	global_load_dword v12, v16, s[74:75] sc1
	global_load_dword v13, v16, s[84:85] sc1
	global_load_dword v14, v16, s[86:87] sc1
	s_mov_b64 s[90:91], -1
	s_mov_b64 s[40:41], -1
	s_waitcnt vmcnt(14)
	v_add_u32_e32 v17, v0, v15
	s_waitcnt vmcnt(13)
	v_add_u32_e32 v17, v17, v1
	s_waitcnt vmcnt(12)
	v_add_u32_e32 v17, v17, v2
	s_waitcnt vmcnt(11)
	v_add_u32_e32 v17, v17, v3
	s_waitcnt vmcnt(10)
	v_add_u32_e32 v17, v17, v4
	s_waitcnt vmcnt(9)
	v_add_u32_e32 v17, v17, v5
	s_waitcnt vmcnt(8)
	v_add_u32_e32 v17, v17, v6
	s_waitcnt vmcnt(7)
	v_add_u32_e32 v17, v17, v7
	s_waitcnt vmcnt(6)
	v_add_u32_e32 v17, v17, v8
	s_waitcnt vmcnt(5)
	v_add_u32_e32 v17, v17, v9
	s_waitcnt vmcnt(4)
	v_add_u32_e32 v17, v17, v10
	s_waitcnt vmcnt(3)
	v_add_u32_e32 v17, v17, v11
	s_waitcnt vmcnt(2)
	v_add_u32_e32 v17, v17, v12
	s_waitcnt vmcnt(1)
	v_add_u32_e32 v17, v17, v13
	s_waitcnt vmcnt(0)
	v_add_u32_e32 v17, v17, v14
	v_cmp_eq_u32_e32 vcc, s6, v17
	s_cbranch_vccnz .LBB0_1205
	s_and_b32 s4, s2, 0xff
	s_cmp_eq_u32 s4, 0
	s_mov_b64 s[4:5], -1
	s_cbranch_scc1 .LBB0_1210
	s_and_b64 vcc, exec, s[4:5]
	s_cbranch_vccz .LBB0_1205

.LBB0_1224:
	s_and_b32 s6, s2, 0xff
	s_mov_b64 s[4:5], -1
	s_cmp_lg_u32 s6, 0
	s_mov_b64 s[42:43], -1
	s_cbranch_scc0 .LBB0_1227
	s_and_b64 vcc, exec, s[42:43]
	s_cbranch_vccz .LBB0_1223

.LBB0_1241:
	s_and_b32 s4, s2, 0xff
	s_cmp_lg_u32 s4, 0
	s_mov_b64 s[40:41], -1
	s_cbranch_scc0 .LBB0_1244
	s_mov_b64 s[42:43], -1
	s_and_b64 vcc, exec, s[40:41]
	s_cbranch_vccz .LBB0_1240

.LBB0_1267:
	global_load_dword v15, v16, s[10:11] sc1
	s_waitcnt lgkmcnt(0)
	global_load_dword v0, v16, s[12:13] sc1
	global_load_dword v1, v16, s[14:15] sc1
	global_load_dword v2, v16, s[24:25] sc1
	global_load_dword v3, v16, s[26:27] sc1
	global_load_dword v4, v16, s[38:39] sc1
	global_load_dword v5, v16, s[42:43] sc1
	global_load_dword v6, v16, s[44:45] sc1
	global_load_dword v7, v16, s[46:47] sc1
	global_load_dword v8, v16, s[48:49] sc1
	global_load_dword v9, v16, s[50:51] sc1
	global_load_dword v10, v16, s[54:55] sc1
	global_load_dword v11, v16, s[64:65] sc1
	global_load_dword v12, v16, s[74:75] sc1
	global_load_dword v13, v16, s[84:85] sc1
	global_load_dword v14, v16, s[86:87] sc1
	s_mov_b64 s[90:91], -1
	s_mov_b64 s[40:41], -1
	s_waitcnt vmcnt(14)
	v_add_u32_e32 v17, v0, v15
	s_waitcnt vmcnt(13)
	v_add_u32_e32 v17, v17, v1
	s_waitcnt vmcnt(12)
	v_add_u32_e32 v17, v17, v2
	s_waitcnt vmcnt(11)
	v_add_u32_e32 v17, v17, v3
	s_waitcnt vmcnt(10)
	v_add_u32_e32 v17, v17, v4
	s_waitcnt vmcnt(9)
	v_add_u32_e32 v17, v17, v5
	s_waitcnt vmcnt(8)
	v_add_u32_e32 v17, v17, v6
	s_waitcnt vmcnt(7)
	v_add_u32_e32 v17, v17, v7
	s_waitcnt vmcnt(6)
	v_add_u32_e32 v17, v17, v8
	s_waitcnt vmcnt(5)
	v_add_u32_e32 v17, v17, v9
	s_waitcnt vmcnt(4)
	v_add_u32_e32 v17, v17, v10
	s_waitcnt vmcnt(3)
	v_add_u32_e32 v17, v17, v11
	s_waitcnt vmcnt(2)
	v_add_u32_e32 v17, v17, v12
	s_waitcnt vmcnt(1)
	v_add_u32_e32 v17, v17, v13
	s_waitcnt vmcnt(0)
	v_add_u32_e32 v17, v17, v14
	v_cmp_eq_u32_e32 vcc, s2, v17
	s_cbranch_vccnz .LBB0_1266
	s_and_b32 s4, s6, 0xff
	s_cmp_eq_u32 s4, 0
	s_mov_b64 s[4:5], -1
	s_cbranch_scc1 .LBB0_1271
	s_and_b64 vcc, exec, s[4:5]
	s_cbranch_vccz .LBB0_1266

.LBB0_1511:
	global_load_dword v15, v16, s[10:11] sc1
	s_waitcnt lgkmcnt(0)
	global_load_dword v0, v16, s[14:15] sc1
	global_load_dword v1, v16, s[24:25] sc1
	global_load_dword v2, v16, s[38:39] sc1
	global_load_dword v3, v16, s[42:43] sc1
	global_load_dword v4, v16, s[44:45] sc1
	global_load_dword v5, v16, s[46:47] sc1
	global_load_dword v6, v16, s[48:49] sc1
	global_load_dword v7, v16, s[50:51] sc1
	global_load_dword v8, v16, s[54:55] sc1
	global_load_dword v9, v16, s[64:65] sc1
	global_load_dword v10, v16, s[74:75] sc1
	global_load_dword v11, v16, s[80:81] sc1
	global_load_dword v12, v16, s[84:85] sc1
	global_load_dword v13, v16, s[86:87] sc1
	global_load_dword v14, v16, s[90:91] sc1
	s_mov_b64 s[40:41], -1
	s_mov_b64 s[4:5], -1
	s_waitcnt vmcnt(14)
	v_add_u32_e32 v17, v0, v15
	s_waitcnt vmcnt(13)
	v_add_u32_e32 v17, v17, v1
	s_waitcnt vmcnt(12)
	v_add_u32_e32 v17, v17, v2
	s_waitcnt vmcnt(11)
	v_add_u32_e32 v17, v17, v3
	s_waitcnt vmcnt(10)
	v_add_u32_e32 v17, v17, v4
	s_waitcnt vmcnt(9)
	v_add_u32_e32 v17, v17, v5
	s_waitcnt vmcnt(8)
	v_add_u32_e32 v17, v17, v6
	s_waitcnt vmcnt(7)
	v_add_u32_e32 v17, v17, v7
	s_waitcnt vmcnt(6)
	v_add_u32_e32 v17, v17, v8
	s_waitcnt vmcnt(5)
	v_add_u32_e32 v17, v17, v9
	s_waitcnt vmcnt(4)
	v_add_u32_e32 v17, v17, v10
	s_waitcnt vmcnt(3)
	v_add_u32_e32 v17, v17, v11
	s_waitcnt vmcnt(2)
	v_add_u32_e32 v17, v17, v12
	s_waitcnt vmcnt(1)
	v_add_u32_e32 v17, v17, v13
	s_waitcnt vmcnt(0)
	v_add_u32_e32 v17, v17, v14
	v_cmp_eq_u32_e32 vcc, s2, v17
	s_cbranch_vccnz .LBB0_1510
	s_and_b32 s7, s6, 0xff
	s_cmp_eq_u32 s7, 0
	s_mov_b64 vcc, -1
	s_cbranch_scc1 .LBB0_1515
	s_and_b64 vcc, exec, vcc
	s_cbranch_vccz .LBB0_1510

.LBB0_1529:
	s_and_b32 s6, s2, 0xff
	s_mov_b64 s[4:5], -1
	s_cmp_lg_u32 s6, 0
	s_mov_b64 s[46:47], -1
	s_cbranch_scc0 .LBB0_1532
	s_and_b64 vcc, exec, s[46:47]
	s_cbranch_vccz .LBB0_1528

.LBB0_1546:
	s_and_b32 s4, s2, 0xff
	s_cmp_lg_u32 s4, 0
	s_mov_b64 s[40:41], -1
	s_cbranch_scc0 .LBB0_1549
	s_mov_b64 s[46:47], -1
	s_and_b64 vcc, exec, s[40:41]
	s_cbranch_vccz .LBB0_1545

.LBB0_1701:
	global_load_dword v15, v16, s[10:11] sc1
	s_waitcnt lgkmcnt(0)
	global_load_dword v0, v16, s[12:13] sc1
	global_load_dword v1, v16, s[14:15] sc1
	global_load_dword v2, v16, s[24:25] sc1
	global_load_dword v3, v16, s[38:39] sc1
	global_load_dword v4, v16, s[42:43] sc1
	global_load_dword v5, v16, s[44:45] sc1
	global_load_dword v6, v16, s[46:47] sc1
	global_load_dword v7, v16, s[48:49] sc1
	global_load_dword v8, v16, s[50:51] sc1
	global_load_dword v9, v16, s[54:55] sc1
	global_load_dword v10, v16, s[64:65] sc1
	global_load_dword v11, v16, s[74:75] sc1
	global_load_dword v12, v16, s[80:81] sc1
	global_load_dword v13, v16, s[84:85] sc1
	global_load_dword v14, v16, s[86:87] sc1
	s_mov_b64 s[40:41], -1
	s_mov_b64 s[4:5], -1
	s_waitcnt vmcnt(14)
	v_add_u32_e32 v17, v0, v15
	s_waitcnt vmcnt(13)
	v_add_u32_e32 v17, v17, v1
	s_waitcnt vmcnt(12)
	v_add_u32_e32 v17, v17, v2
	s_waitcnt vmcnt(11)
	v_add_u32_e32 v17, v17, v3
	s_waitcnt vmcnt(10)
	v_add_u32_e32 v17, v17, v4
	s_waitcnt vmcnt(9)
	v_add_u32_e32 v17, v17, v5
	s_waitcnt vmcnt(8)
	v_add_u32_e32 v17, v17, v6
	s_waitcnt vmcnt(7)
	v_add_u32_e32 v17, v17, v7
	s_waitcnt vmcnt(6)
	v_add_u32_e32 v17, v17, v8
	s_waitcnt vmcnt(5)
	v_add_u32_e32 v17, v17, v9
	s_waitcnt vmcnt(4)
	v_add_u32_e32 v17, v17, v10
	s_waitcnt vmcnt(3)
	v_add_u32_e32 v17, v17, v11
	s_waitcnt vmcnt(2)
	v_add_u32_e32 v17, v17, v12
	s_waitcnt vmcnt(1)
	v_add_u32_e32 v17, v17, v13
	s_waitcnt vmcnt(0)
	v_add_u32_e32 v17, v17, v14
	v_cmp_eq_u32_e32 vcc, s2, v17
	s_cbranch_vccnz .LBB0_1700
	s_and_b32 s7, s6, 0xff
	s_cmp_eq_u32 s7, 0
	s_mov_b64 s[90:91], -1
	s_cbranch_scc1 .LBB0_1705
	s_and_b64 vcc, exec, s[90:91]
	s_cbranch_vccz .LBB0_1700

.LBB0_1796:
	global_load_dword v15, v16, s[10:11] sc1
	s_waitcnt lgkmcnt(0)
	global_load_dword v0, v16, s[12:13] sc1
	global_load_dword v1, v16, s[14:15] sc1
	global_load_dword v2, v16, s[24:25] sc1
	global_load_dword v3, v16, s[38:39] sc1
	global_load_dword v4, v16, s[42:43] sc1
	global_load_dword v5, v16, s[44:45] sc1
	global_load_dword v6, v16, s[46:47] sc1
	global_load_dword v7, v16, s[48:49] sc1
	global_load_dword v8, v16, s[50:51] sc1
	global_load_dword v9, v16, s[54:55] sc1
	global_load_dword v10, v16, s[64:65] sc1
	global_load_dword v11, v16, s[74:75] sc1
	global_load_dword v12, v16, s[80:81] sc1
	global_load_dword v13, v16, s[82:83] sc1
	global_load_dword v14, v16, s[84:85] sc1
	s_mov_b64 s[40:41], -1
	s_mov_b64 s[4:5], -1
	s_waitcnt vmcnt(14)
	v_add_u32_e32 v17, v0, v15
	s_waitcnt vmcnt(13)
	v_add_u32_e32 v17, v17, v1
	s_waitcnt vmcnt(12)
	v_add_u32_e32 v17, v17, v2
	s_waitcnt vmcnt(11)
	v_add_u32_e32 v17, v17, v3
	s_waitcnt vmcnt(10)
	v_add_u32_e32 v17, v17, v4
	s_waitcnt vmcnt(9)
	v_add_u32_e32 v17, v17, v5
	s_waitcnt vmcnt(8)
	v_add_u32_e32 v17, v17, v6
	s_waitcnt vmcnt(7)
	v_add_u32_e32 v17, v17, v7
	s_waitcnt vmcnt(6)
	v_add_u32_e32 v17, v17, v8
	s_waitcnt vmcnt(5)
	v_add_u32_e32 v17, v17, v9
	s_waitcnt vmcnt(4)
	v_add_u32_e32 v17, v17, v10
	s_waitcnt vmcnt(3)
	v_add_u32_e32 v17, v17, v11
	s_waitcnt vmcnt(2)
	v_add_u32_e32 v17, v17, v12
	s_waitcnt vmcnt(1)
	v_add_u32_e32 v17, v17, v13
	s_waitcnt vmcnt(0)
	v_add_u32_e32 v17, v17, v14
	v_cmp_eq_u32_e32 vcc, s2, v17
	s_cbranch_vccnz .LBB0_1795
	s_and_b32 s7, s6, 0xff
	s_cmp_eq_u32 s7, 0
	s_mov_b64 s[86:87], -1
	s_cbranch_scc1 .LBB0_1800
	s_and_b64 vcc, exec, s[86:87]
	s_cbranch_vccz .LBB0_1795

.LBB0_1925:
	global_load_dword v15, v16, s[12:13] sc1
	global_load_dword v0, v16, s[14:15] sc1
	global_load_dword v1, v16, s[18:19] sc1
	global_load_dword v2, v16, s[24:25] sc1
	global_load_dword v3, v16, s[38:39] sc1
	global_load_dword v4, v16, s[40:41] sc1
	global_load_dword v5, v16, s[42:43] sc1
	global_load_dword v6, v16, s[44:45] sc1
	global_load_dword v7, v16, s[46:47] sc1
	global_load_dword v8, v16, s[48:49] sc1
	global_load_dword v9, v16, s[50:51] sc1
	global_load_dword v10, v16, s[54:55] sc1
	global_load_dword v11, v16, s[64:65] sc1
	global_load_dword v12, v16, s[74:75] sc1
	global_load_dword v13, v16, s[80:81] sc1
	global_load_dword v14, v16, s[82:83] sc1
	s_mov_b64 s[84:85], -1
	s_mov_b64 s[4:5], -1
	s_waitcnt vmcnt(14)
	v_add_u32_e32 v17, v0, v15
	s_waitcnt vmcnt(13)
	v_add_u32_e32 v17, v17, v1
	s_waitcnt vmcnt(12)
	v_add_u32_e32 v17, v17, v2
	s_waitcnt vmcnt(11)
	v_add_u32_e32 v17, v17, v3
	s_waitcnt vmcnt(10)
	v_add_u32_e32 v17, v17, v4
	s_waitcnt vmcnt(9)
	v_add_u32_e32 v17, v17, v5
	s_waitcnt vmcnt(8)
	v_add_u32_e32 v17, v17, v6
	s_waitcnt vmcnt(7)
	v_add_u32_e32 v17, v17, v7
	s_waitcnt vmcnt(6)
	v_add_u32_e32 v17, v17, v8
	s_waitcnt vmcnt(5)
	v_add_u32_e32 v17, v17, v9
	s_waitcnt vmcnt(4)
	v_add_u32_e32 v17, v17, v10
	s_waitcnt vmcnt(3)
	v_add_u32_e32 v17, v17, v11
	s_waitcnt vmcnt(2)
	v_add_u32_e32 v17, v17, v12
	s_waitcnt vmcnt(1)
	v_add_u32_e32 v17, v17, v13
	s_waitcnt vmcnt(0)
	v_add_u32_e32 v17, v17, v14
	v_cmp_eq_u32_e32 vcc, s6, v17
	s_cbranch_vccnz .LBB0_1924
	s_and_b32 s7, s2, 0xff
	s_cmp_eq_u32 s7, 0
	s_mov_b64 s[86:87], -1
	s_cbranch_scc1 .LBB0_1929
	s_and_b64 vcc, exec, s[86:87]
	s_cbranch_vccz .LBB0_1924

.LBB0_2024:
	global_load_dword v15, v16, s[12:13] sc1
	global_load_dword v0, v16, s[14:15] sc1
	global_load_dword v1, v16, s[16:17] sc1
	global_load_dword v2, v16, s[18:19] sc1
	global_load_dword v3, v16, s[24:25] sc1
	global_load_dword v4, v16, s[38:39] sc1
	global_load_dword v5, v16, s[40:41] sc1
	global_load_dword v6, v16, s[42:43] sc1
	global_load_dword v7, v16, s[44:45] sc1
	global_load_dword v8, v16, s[46:47] sc1
	global_load_dword v9, v16, s[48:49] sc1
	global_load_dword v10, v16, s[50:51] sc1
	global_load_dword v11, v16, s[54:55] sc1
	global_load_dword v12, v16, s[64:65] sc1
	global_load_dword v13, v16, s[74:75] sc1
	global_load_dword v14, v16, s[80:81] sc1
	s_mov_b64 s[82:83], -1
	s_mov_b64 s[4:5], -1
	s_waitcnt vmcnt(14)
	v_add_u32_e32 v17, v0, v15
	s_waitcnt vmcnt(13)
	v_add_u32_e32 v17, v17, v1
	s_waitcnt vmcnt(12)
	v_add_u32_e32 v17, v17, v2
	s_waitcnt vmcnt(11)
	v_add_u32_e32 v17, v17, v3
	s_waitcnt vmcnt(10)
	v_add_u32_e32 v17, v17, v4
	s_waitcnt vmcnt(9)
	v_add_u32_e32 v17, v17, v5
	s_waitcnt vmcnt(8)
	v_add_u32_e32 v17, v17, v6
	s_waitcnt vmcnt(7)
	v_add_u32_e32 v17, v17, v7
	s_waitcnt vmcnt(6)
	v_add_u32_e32 v17, v17, v8
	s_waitcnt vmcnt(5)
	v_add_u32_e32 v17, v17, v9
	s_waitcnt vmcnt(4)
	v_add_u32_e32 v17, v17, v10
	s_waitcnt vmcnt(3)
	v_add_u32_e32 v17, v17, v11
	s_waitcnt vmcnt(2)
	v_add_u32_e32 v17, v17, v12
	s_waitcnt vmcnt(1)
	v_add_u32_e32 v17, v17, v13
	s_waitcnt vmcnt(0)
	v_add_u32_e32 v17, v17, v14
	v_cmp_eq_u32_e32 vcc, s6, v17
	s_cbranch_vccnz .LBB0_2023
	s_and_b32 s7, s2, 0xff
	s_cmp_eq_u32 s7, 0
	s_mov_b64 s[84:85], -1
	s_cbranch_scc1 .LBB0_2028
	s_and_b64 vcc, exec, s[84:85]
	s_cbranch_vccz .LBB0_2023

.LBB0_2085:
	global_load_dword v15, v16, s[12:13] sc1
	s_waitcnt lgkmcnt(0)
	global_load_dword v0, v16, s[14:15] sc1
	global_load_dword v1, v16, s[16:17] sc1
	global_load_dword v2, v16, s[18:19] sc1
	global_load_dword v3, v16, s[24:25] sc1
	global_load_dword v4, v16, s[38:39] sc1
	global_load_dword v5, v16, s[40:41] sc1
	global_load_dword v6, v16, s[42:43] sc1
	global_load_dword v7, v16, s[44:45] sc1
	global_load_dword v8, v16, s[46:47] sc1
	global_load_dword v9, v16, s[48:49] sc1
	global_load_dword v10, v16, s[50:51] sc1
	global_load_dword v11, v16, s[54:55] sc1
	global_load_dword v12, v16, s[64:65] sc1
	global_load_dword v13, v16, s[74:75] sc1
	global_load_dword v14, v16, s[80:81] sc1
	s_mov_b64 s[82:83], -1
	s_mov_b64 s[4:5], -1
	s_waitcnt vmcnt(14)
	v_add_u32_e32 v17, v0, v15
	s_waitcnt vmcnt(13)
	v_add_u32_e32 v17, v17, v1
	s_waitcnt vmcnt(12)
	v_add_u32_e32 v17, v17, v2
	s_waitcnt vmcnt(11)
	v_add_u32_e32 v17, v17, v3
	s_waitcnt vmcnt(10)
	v_add_u32_e32 v17, v17, v4
	s_waitcnt vmcnt(9)
	v_add_u32_e32 v17, v17, v5
	s_waitcnt vmcnt(8)
	v_add_u32_e32 v17, v17, v6
	s_waitcnt vmcnt(7)
	v_add_u32_e32 v17, v17, v7
	s_waitcnt vmcnt(6)
	v_add_u32_e32 v17, v17, v8
	s_waitcnt vmcnt(5)
	v_add_u32_e32 v17, v17, v9
	s_waitcnt vmcnt(4)
	v_add_u32_e32 v17, v17, v10
	s_waitcnt vmcnt(3)
	v_add_u32_e32 v17, v17, v11
	s_waitcnt vmcnt(2)
	v_add_u32_e32 v17, v17, v12
	s_waitcnt vmcnt(1)
	v_add_u32_e32 v17, v17, v13
	s_waitcnt vmcnt(0)
	v_add_u32_e32 v17, v17, v14
	v_cmp_eq_u32_e32 vcc, s2, v17
	s_cbranch_vccnz .LBB0_2084
	s_and_b32 s7, s6, 0xff
	s_cmp_eq_u32 s7, 0
	s_mov_b64 s[84:85], -1
	s_cbranch_scc1 .LBB0_2089
	s_and_b64 vcc, exec, s[84:85]
	s_cbranch_vccz .LBB0_2084

.LBB0_2410:
	global_load_dword v15, v16, s[14:15] sc1
	s_waitcnt lgkmcnt(0)
	global_load_dword v0, v16, s[16:17] sc1
	global_load_dword v1, v16, s[18:19] sc1
	global_load_dword v2, v16, s[24:25] sc1
	global_load_dword v3, v16, s[40:41] sc1
	global_load_dword v4, v16, s[42:43] sc1
	global_load_dword v5, v16, s[44:45] sc1
	global_load_dword v6, v16, s[46:47] sc1
	global_load_dword v7, v16, s[48:49] sc1
	global_load_dword v8, v16, s[50:51] sc1
	global_load_dword v9, v16, s[54:55] sc1
	global_load_dword v10, v16, s[64:65] sc1
	global_load_dword v11, v16, s[74:75] sc1
	global_load_dword v12, v16, s[78:79] sc1
	global_load_dword v13, v16, s[80:81] sc1
	global_load_dword v14, v16, s[82:83] sc1
	s_mov_b64 s[84:85], -1
	s_mov_b64 s[4:5], -1
	s_waitcnt vmcnt(14)
	v_add_u32_e32 v17, v0, v15
	s_waitcnt vmcnt(13)
	v_add_u32_e32 v17, v17, v1
	s_waitcnt vmcnt(12)
	v_add_u32_e32 v17, v17, v2
	s_waitcnt vmcnt(11)
	v_add_u32_e32 v17, v17, v3
	s_waitcnt vmcnt(10)
	v_add_u32_e32 v17, v17, v4
	s_waitcnt vmcnt(9)
	v_add_u32_e32 v17, v17, v5
	s_waitcnt vmcnt(8)
	v_add_u32_e32 v17, v17, v6
	s_waitcnt vmcnt(7)
	v_add_u32_e32 v17, v17, v7
	s_waitcnt vmcnt(6)
	v_add_u32_e32 v17, v17, v8
	s_waitcnt vmcnt(5)
	v_add_u32_e32 v17, v17, v9
	s_waitcnt vmcnt(4)
	v_add_u32_e32 v17, v17, v10
	s_waitcnt vmcnt(3)
	v_add_u32_e32 v17, v17, v11
	s_waitcnt vmcnt(2)
	v_add_u32_e32 v17, v17, v12
	s_waitcnt vmcnt(1)
	v_add_u32_e32 v17, v17, v13
	s_waitcnt vmcnt(0)
	v_add_u32_e32 v17, v17, v14
	v_cmp_eq_u32_e32 vcc, s2, v17
	s_cbranch_vccnz .LBB0_2409
	s_and_b32 s7, s6, 0xff
	s_cmp_eq_u32 s7, 0
	s_mov_b64 s[86:87], -1
	s_cbranch_scc1 .LBB0_2414
	s_and_b64 vcc, exec, s[86:87]
	s_cbranch_vccz .LBB0_2409

.LBB0_2445:
	s_and_b32 s4, s2, 0xff
	s_cmp_lg_u32 s4, 0
	s_mov_b64 s[44:45], -1
	s_cbranch_scc0 .LBB0_2448
	s_mov_b64 s[46:47], -1
	s_and_b64 vcc, exec, s[44:45]
	s_cbranch_vccz .LBB0_2444

.LBB0_2471:
	global_load_dword v15, v16, s[12:13] sc1
	s_waitcnt lgkmcnt(0)
	global_load_dword v0, v16, s[14:15] sc1
	global_load_dword v1, v16, s[16:17] sc1
	global_load_dword v2, v16, s[18:19] sc1
	global_load_dword v3, v16, s[24:25] sc1
	global_load_dword v4, v16, s[44:45] sc1
	global_load_dword v5, v16, s[46:47] sc1
	global_load_dword v6, v16, s[48:49] sc1
	global_load_dword v7, v16, s[50:51] sc1
	global_load_dword v8, v16, s[54:55] sc1
	global_load_dword v9, v16, s[64:65] sc1
	global_load_dword v10, v16, s[74:75] sc1
	global_load_dword v11, v16, s[78:79] sc1
	global_load_dword v12, v16, s[80:81] sc1
	global_load_dword v13, v16, s[82:83] sc1
	global_load_dword v14, v16, s[84:85] sc1
	s_mov_b64 s[86:87], -1
	s_mov_b64 s[4:5], -1
	s_waitcnt vmcnt(14)
	v_add_u32_e32 v17, v0, v15
	s_waitcnt vmcnt(13)
	v_add_u32_e32 v17, v17, v1
	s_waitcnt vmcnt(12)
	v_add_u32_e32 v17, v17, v2
	s_waitcnt vmcnt(11)
	v_add_u32_e32 v17, v17, v3
	s_waitcnt vmcnt(10)
	v_add_u32_e32 v17, v17, v4
	s_waitcnt vmcnt(9)
	v_add_u32_e32 v17, v17, v5
	s_waitcnt vmcnt(8)
	v_add_u32_e32 v17, v17, v6
	s_waitcnt vmcnt(7)
	v_add_u32_e32 v17, v17, v7
	s_waitcnt vmcnt(6)
	v_add_u32_e32 v17, v17, v8
	s_waitcnt vmcnt(5)
	v_add_u32_e32 v17, v17, v9
	s_waitcnt vmcnt(4)
	v_add_u32_e32 v17, v17, v10
	s_waitcnt vmcnt(3)
	v_add_u32_e32 v17, v17, v11
	s_waitcnt vmcnt(2)
	v_add_u32_e32 v17, v17, v12
	s_waitcnt vmcnt(1)
	v_add_u32_e32 v17, v17, v13
	s_waitcnt vmcnt(0)
	v_add_u32_e32 v17, v17, v14
	v_cmp_eq_u32_e32 vcc, s2, v17
	s_cbranch_vccnz .LBB0_2470
	s_and_b32 s7, s6, 0xff
	s_cmp_eq_u32 s7, 0
	s_mov_b64 s[90:91], -1
	s_cbranch_scc1 .LBB0_2475
	s_and_b64 vcc, exec, s[90:91]
	s_cbranch_vccz .LBB0_2470

.LBB0_2489:
	s_and_b32 s6, s2, 0xff
	s_mov_b64 s[4:5], -1
	s_cmp_lg_u32 s6, 0
	s_mov_b64 s[48:49], -1
	s_cbranch_scc0 .LBB0_2492
	s_and_b64 vcc, exec, s[48:49]
	s_cbranch_vccz .LBB0_2488

.LBB0_2506:
	s_and_b32 s4, s2, 0xff
	s_cmp_lg_u32 s4, 0
	s_mov_b64 s[46:47], -1
	s_cbranch_scc0 .LBB0_2509
	s_mov_b64 s[48:49], -1
	s_and_b64 vcc, exec, s[46:47]
	s_cbranch_vccz .LBB0_2505

.LBB0_2643:
	global_load_dword v15, v16, s[16:17] sc1
	s_waitcnt lgkmcnt(0)
	global_load_dword v0, v16, s[18:19] sc1
	global_load_dword v1, v16, s[20:21] sc1
	global_load_dword v2, v16, s[22:23] sc1
	global_load_dword v3, v16, s[24:25] sc1
	global_load_dword v4, v16, s[38:39] sc1
	global_load_dword v5, v16, s[40:41] sc1
	global_load_dword v6, v16, s[42:43] sc1
	global_load_dword v7, v16, s[44:45] sc1
	global_load_dword v8, v16, s[46:47] sc1
	global_load_dword v9, v16, s[48:49] sc1
	global_load_dword v10, v16, s[50:51] sc1
	global_load_dword v11, v16, s[54:55] sc1
	global_load_dword v12, v16, s[64:65] sc1
	global_load_dword v13, v16, s[74:75] sc1
	global_load_dword v14, v16, s[78:79] sc1
	s_mov_b64 s[80:81], -1
	s_mov_b64 s[4:5], -1
	s_waitcnt vmcnt(14)
	v_add_u32_e32 v17, v0, v15
	s_waitcnt vmcnt(13)
	v_add_u32_e32 v17, v17, v1
	s_waitcnt vmcnt(12)
	v_add_u32_e32 v17, v17, v2
	s_waitcnt vmcnt(11)
	v_add_u32_e32 v17, v17, v3
	s_waitcnt vmcnt(10)
	v_add_u32_e32 v17, v17, v4
	s_waitcnt vmcnt(9)
	v_add_u32_e32 v17, v17, v5
	s_waitcnt vmcnt(8)
	v_add_u32_e32 v17, v17, v6
	s_waitcnt vmcnt(7)
	v_add_u32_e32 v17, v17, v7
	s_waitcnt vmcnt(6)
	v_add_u32_e32 v17, v17, v8
	s_waitcnt vmcnt(5)
	v_add_u32_e32 v17, v17, v9
	s_waitcnt vmcnt(4)
	v_add_u32_e32 v17, v17, v10
	s_waitcnt vmcnt(3)
	v_add_u32_e32 v17, v17, v11
	s_waitcnt vmcnt(2)
	v_add_u32_e32 v17, v17, v12
	s_waitcnt vmcnt(1)
	v_add_u32_e32 v17, v17, v13
	s_waitcnt vmcnt(0)
	v_add_u32_e32 v17, v17, v14
	v_cmp_eq_u32_e32 vcc, s2, v17
	s_cbranch_vccnz .LBB0_2642
	s_and_b32 s7, s6, 0xff
	s_cmp_eq_u32 s7, 0
	s_mov_b64 s[82:83], -1
	s_cbranch_scc1 .LBB0_2647
	s_and_b64 vcc, exec, s[82:83]
	s_cbranch_vccz .LBB0_2641

.LBB0_2736:
	global_load_dword v15, v16, s[12:13] sc1
	s_waitcnt lgkmcnt(0)
	global_load_dword v0, v16, s[14:15] sc1
	global_load_dword v1, v16, s[16:17] sc1
	global_load_dword v2, v16, s[18:19] sc1
	global_load_dword v3, v16, s[20:21] sc1
	global_load_dword v4, v16, s[22:23] sc1
	global_load_dword v5, v16, s[24:25] sc1
	global_load_dword v6, v16, s[26:27] sc1
	global_load_dword v7, v16, s[38:39] sc1
	global_load_dword v8, v16, s[40:41] sc1
	global_load_dword v9, v16, s[42:43] sc1
	global_load_dword v10, v16, s[44:45] sc1
	global_load_dword v11, v16, s[46:47] sc1
	global_load_dword v12, v16, s[48:49] sc1
	global_load_dword v13, v16, s[50:51] sc1
	global_load_dword v14, v16, s[54:55] sc1
	s_mov_b64 s[64:65], -1
	s_mov_b64 s[4:5], -1
	s_waitcnt vmcnt(14)
	v_add_u32_e32 v17, v0, v15
	s_waitcnt vmcnt(13)
	v_add_u32_e32 v17, v17, v1
	s_waitcnt vmcnt(12)
	v_add_u32_e32 v17, v17, v2
	s_waitcnt vmcnt(11)
	v_add_u32_e32 v17, v17, v3
	s_waitcnt vmcnt(10)
	v_add_u32_e32 v17, v17, v4
	s_waitcnt vmcnt(9)
	v_add_u32_e32 v17, v17, v5
	s_waitcnt vmcnt(8)
	v_add_u32_e32 v17, v17, v6
	s_waitcnt vmcnt(7)
	v_add_u32_e32 v17, v17, v7
	s_waitcnt vmcnt(6)
	v_add_u32_e32 v17, v17, v8
	s_waitcnt vmcnt(5)
	v_add_u32_e32 v17, v17, v9
	s_waitcnt vmcnt(4)
	v_add_u32_e32 v17, v17, v10
	s_waitcnt vmcnt(3)
	v_add_u32_e32 v17, v17, v11
	s_waitcnt vmcnt(2)
	v_add_u32_e32 v17, v17, v12
	s_waitcnt vmcnt(1)
	v_add_u32_e32 v17, v17, v13
	s_waitcnt vmcnt(0)
	v_add_u32_e32 v17, v17, v14
	v_cmp_eq_u32_e32 vcc, s2, v17
	s_cbranch_vccnz .LBB0_2735
	s_and_b32 s7, s6, 0xff
	s_cmp_eq_u32 s7, 0
	s_mov_b64 s[74:75], -1
	s_cbranch_scc1 .LBB0_2740
	s_and_b64 vcc, exec, s[74:75]
	s_cbranch_vccz .LBB0_2735

.LBB0_2754:
	s_and_b32 s6, s2, 0xff
	s_mov_b64 s[4:5], -1
	s_cmp_lg_u32 s6, 0
	s_mov_b64 s[26:27], -1
	s_cbranch_scc0 .LBB0_2757
	s_and_b64 vcc, exec, s[26:27]
	s_cbranch_vccz .LBB0_2753

.LBB0_2771:
	s_and_b32 s4, s2, 0xff
	s_cmp_lg_u32 s4, 0
	s_mov_b64 s[24:25], -1
	s_cbranch_scc0 .LBB0_2774
	s_mov_b64 s[26:27], -1
	s_and_b64 vcc, exec, s[24:25]
	s_cbranch_vccz .LBB0_2770

.LBB0_2831:
	global_load_dword v15, v16, s[12:13] sc1
	s_waitcnt lgkmcnt(0)
	global_load_dword v0, v16, s[14:15] sc1
	global_load_dword v1, v16, s[16:17] sc1
	global_load_dword v2, v16, s[18:19] sc1
	global_load_dword v3, v16, s[20:21] sc1
	global_load_dword v4, v16, s[22:23] sc1
	global_load_dword v5, v16, s[24:25] sc1
	global_load_dword v6, v16, s[26:27] sc1
	global_load_dword v7, v16, s[36:37] sc1
	global_load_dword v8, v16, s[38:39] sc1
	global_load_dword v9, v16, s[40:41] sc1
	global_load_dword v10, v16, s[42:43] sc1
	global_load_dword v11, v16, s[44:45] sc1
	global_load_dword v12, v16, s[46:47] sc1
	global_load_dword v13, v16, s[48:49] sc1
	global_load_dword v14, v16, s[50:51] sc1
	s_mov_b64 s[54:55], -1
	s_mov_b64 s[4:5], -1
	s_waitcnt vmcnt(14)
	v_add_u32_e32 v17, v0, v15
	s_waitcnt vmcnt(13)
	v_add_u32_e32 v17, v17, v1
	s_waitcnt vmcnt(12)
	v_add_u32_e32 v17, v17, v2
	s_waitcnt vmcnt(11)
	v_add_u32_e32 v17, v17, v3
	s_waitcnt vmcnt(10)
	v_add_u32_e32 v17, v17, v4
	s_waitcnt vmcnt(9)
	v_add_u32_e32 v17, v17, v5
	s_waitcnt vmcnt(8)
	v_add_u32_e32 v17, v17, v6
	s_waitcnt vmcnt(7)
	v_add_u32_e32 v17, v17, v7
	s_waitcnt vmcnt(6)
	v_add_u32_e32 v17, v17, v8
	s_waitcnt vmcnt(5)
	v_add_u32_e32 v17, v17, v9
	s_waitcnt vmcnt(4)
	v_add_u32_e32 v17, v17, v10
	s_waitcnt vmcnt(3)
	v_add_u32_e32 v17, v17, v11
	s_waitcnt vmcnt(2)
	v_add_u32_e32 v17, v17, v12
	s_waitcnt vmcnt(1)
	v_add_u32_e32 v17, v17, v13
	s_waitcnt vmcnt(0)
	v_add_u32_e32 v17, v17, v14
	v_cmp_eq_u32_e32 vcc, s2, v17
	s_cbranch_vccnz .LBB0_2830
	s_and_b32 s7, s6, 0xff
	s_cmp_eq_u32 s7, 0
	s_mov_b64 s[64:65], -1
	s_cbranch_scc1 .LBB0_2835
	s_and_b64 vcc, exec, s[64:65]
	s_cbranch_vccz .LBB0_2830

.LBB0_2960:
	global_load_dword v15, v16, s[10:11] sc1
	global_load_dword v0, v16, s[12:13] sc1
	global_load_dword v1, v16, s[14:15] sc1
	global_load_dword v2, v16, s[16:17] sc1
	global_load_dword v3, v16, s[18:19] sc1
	global_load_dword v4, v16, s[20:21] sc1
	global_load_dword v5, v16, s[22:23] sc1
	global_load_dword v6, v16, s[24:25] sc1
	global_load_dword v7, v16, s[26:27] sc1
	global_load_dword v8, v16, s[34:35] sc1
	global_load_dword v9, v16, s[36:37] sc1
	global_load_dword v10, v16, s[38:39] sc1
	global_load_dword v11, v16, s[40:41] sc1
	global_load_dword v12, v16, s[42:43] sc1
	global_load_dword v13, v16, s[44:45] sc1
	global_load_dword v14, v16, s[46:47] sc1
	s_mov_b64 s[48:49], -1
	s_mov_b64 s[4:5], -1
	s_waitcnt vmcnt(14)
	v_add_u32_e32 v17, v0, v15
	s_waitcnt vmcnt(13)
	v_add_u32_e32 v17, v17, v1
	s_waitcnt vmcnt(12)
	v_add_u32_e32 v17, v17, v2
	s_waitcnt vmcnt(11)
	v_add_u32_e32 v17, v17, v3
	s_waitcnt vmcnt(10)
	v_add_u32_e32 v17, v17, v4
	s_waitcnt vmcnt(9)
	v_add_u32_e32 v17, v17, v5
	s_waitcnt vmcnt(8)
	v_add_u32_e32 v17, v17, v6
	s_waitcnt vmcnt(7)
	v_add_u32_e32 v17, v17, v7
	s_waitcnt vmcnt(6)
	v_add_u32_e32 v17, v17, v8
	s_waitcnt vmcnt(5)
	v_add_u32_e32 v17, v17, v9
	s_waitcnt vmcnt(4)
	v_add_u32_e32 v17, v17, v10
	s_waitcnt vmcnt(3)
	v_add_u32_e32 v17, v17, v11
	s_waitcnt vmcnt(2)
	v_add_u32_e32 v17, v17, v12
	s_waitcnt vmcnt(1)
	v_add_u32_e32 v17, v17, v13
	s_waitcnt vmcnt(0)
	v_add_u32_e32 v17, v17, v14
	v_cmp_eq_u32_e32 vcc, s6, v17
	s_cbranch_vccnz .LBB0_2959
	s_and_b32 s7, s2, 0xff
	s_cmp_eq_u32 s7, 0
	s_mov_b64 s[50:51], -1
	s_cbranch_scc1 .LBB0_2964
	s_and_b64 vcc, exec, s[50:51]
	s_cbranch_vccz .LBB0_2959

.LBB0_3059:
	global_load_dword v15, v16, s[10:11] sc1
	global_load_dword v0, v16, s[12:13] sc1
	global_load_dword v1, v16, s[14:15] sc1
	global_load_dword v2, v16, s[16:17] sc1
	global_load_dword v3, v16, s[18:19] sc1
	global_load_dword v4, v16, s[20:21] sc1
	global_load_dword v5, v16, s[22:23] sc1
	global_load_dword v6, v16, s[24:25] sc1
	global_load_dword v7, v16, s[26:27] sc1
	global_load_dword v8, v16, s[30:31] sc1
	global_load_dword v9, v16, s[34:35] sc1
	global_load_dword v10, v16, s[36:37] sc1
	global_load_dword v11, v16, s[38:39] sc1
	global_load_dword v12, v16, s[40:41] sc1
	global_load_dword v13, v16, s[42:43] sc1
	global_load_dword v14, v16, s[44:45] sc1
	s_mov_b64 s[46:47], -1
	s_mov_b64 s[4:5], -1
	s_waitcnt vmcnt(14)
	v_add_u32_e32 v17, v0, v15
	s_waitcnt vmcnt(13)
	v_add_u32_e32 v17, v17, v1
	s_waitcnt vmcnt(12)
	v_add_u32_e32 v17, v17, v2
	s_waitcnt vmcnt(11)
	v_add_u32_e32 v17, v17, v3
	s_waitcnt vmcnt(10)
	v_add_u32_e32 v17, v17, v4
	s_waitcnt vmcnt(9)
	v_add_u32_e32 v17, v17, v5
	s_waitcnt vmcnt(8)
	v_add_u32_e32 v17, v17, v6
	s_waitcnt vmcnt(7)
	v_add_u32_e32 v17, v17, v7
	s_waitcnt vmcnt(6)
	v_add_u32_e32 v17, v17, v8
	s_waitcnt vmcnt(5)
	v_add_u32_e32 v17, v17, v9
	s_waitcnt vmcnt(4)
	v_add_u32_e32 v17, v17, v10
	s_waitcnt vmcnt(3)
	v_add_u32_e32 v17, v17, v11
	s_waitcnt vmcnt(2)
	v_add_u32_e32 v17, v17, v12
	s_waitcnt vmcnt(1)
	v_add_u32_e32 v17, v17, v13
	s_waitcnt vmcnt(0)
	v_add_u32_e32 v17, v17, v14
	v_cmp_eq_u32_e32 vcc, s6, v17
	s_cbranch_vccnz .LBB0_3058
	s_and_b32 s7, s2, 0xff
	s_cmp_eq_u32 s7, 0
	s_mov_b64 s[48:49], -1
	s_cbranch_scc1 .LBB0_3063
	s_and_b64 vcc, exec, s[48:49]
	s_cbranch_vccz .LBB0_3058

.LBB0_3120:
	global_load_dword v15, v16, s[10:11] sc1
	s_waitcnt lgkmcnt(0)
	global_load_dword v0, v16, s[12:13] sc1
	global_load_dword v1, v16, s[14:15] sc1
	global_load_dword v2, v16, s[16:17] sc1
	global_load_dword v3, v16, s[18:19] sc1
	global_load_dword v4, v16, s[20:21] sc1
	global_load_dword v5, v16, s[22:23] sc1
	global_load_dword v6, v16, s[24:25] sc1
	global_load_dword v7, v16, s[26:27] sc1
	global_load_dword v8, v16, s[30:31] sc1
	global_load_dword v9, v16, s[34:35] sc1
	global_load_dword v10, v16, s[36:37] sc1
	global_load_dword v11, v16, s[38:39] sc1
	global_load_dword v12, v16, s[40:41] sc1
	global_load_dword v13, v16, s[42:43] sc1
	global_load_dword v14, v16, s[44:45] sc1
	s_mov_b64 s[46:47], -1
	s_mov_b64 s[4:5], -1
	s_waitcnt vmcnt(14)
	v_add_u32_e32 v17, v0, v15
	s_waitcnt vmcnt(13)
	v_add_u32_e32 v17, v17, v1
	s_waitcnt vmcnt(12)
	v_add_u32_e32 v17, v17, v2
	s_waitcnt vmcnt(11)
	v_add_u32_e32 v17, v17, v3
	s_waitcnt vmcnt(10)
	v_add_u32_e32 v17, v17, v4
	s_waitcnt vmcnt(9)
	v_add_u32_e32 v17, v17, v5
	s_waitcnt vmcnt(8)
	v_add_u32_e32 v17, v17, v6
	s_waitcnt vmcnt(7)
	v_add_u32_e32 v17, v17, v7
	s_waitcnt vmcnt(6)
	v_add_u32_e32 v17, v17, v8
	s_waitcnt vmcnt(5)
	v_add_u32_e32 v17, v17, v9
	s_waitcnt vmcnt(4)
	v_add_u32_e32 v17, v17, v10
	s_waitcnt vmcnt(3)
	v_add_u32_e32 v17, v17, v11
	s_waitcnt vmcnt(2)
	v_add_u32_e32 v17, v17, v12
	s_waitcnt vmcnt(1)
	v_add_u32_e32 v17, v17, v13
	s_waitcnt vmcnt(0)
	v_add_u32_e32 v17, v17, v14
	v_cmp_eq_u32_e32 vcc, s2, v17
	s_cbranch_vccnz .LBB0_3119
	s_and_b32 s7, s6, 0xff
	s_cmp_eq_u32 s7, 0
	s_mov_b64 s[48:49], -1
	s_cbranch_scc1 .LBB0_3124
	s_and_b64 vcc, exec, s[48:49]
	s_cbranch_vccz .LBB0_3119

.LBB0_3254:
	global_load_dword v15, v16, s[10:11] sc1
	s_waitcnt lgkmcnt(0)
	global_load_dword v0, v16, s[12:13] sc1
	global_load_dword v1, v16, s[14:15] sc1
	global_load_dword v2, v16, s[16:17] sc1
	global_load_dword v3, v16, s[18:19] sc1
	global_load_dword v4, v16, s[20:21] sc1
	global_load_dword v5, v16, s[22:23] sc1
	global_load_dword v6, v16, s[24:25] sc1
	global_load_dword v7, v16, s[26:27] sc1
	global_load_dword v8, v16, s[28:29] sc1
	global_load_dword v9, v16, s[30:31] sc1
	global_load_dword v10, v16, s[34:35] sc1
	global_load_dword v11, v16, s[36:37] sc1
	global_load_dword v12, v16, s[38:39] sc1
	global_load_dword v13, v16, s[40:41] sc1
	global_load_dword v14, v16, s[42:43] sc1
	s_mov_b64 s[44:45], -1
	s_mov_b64 s[4:5], -1
	s_waitcnt vmcnt(14)
	v_add_u32_e32 v17, v0, v15
	s_waitcnt vmcnt(13)
	v_add_u32_e32 v17, v17, v1
	s_waitcnt vmcnt(12)
	v_add_u32_e32 v17, v17, v2
	s_waitcnt vmcnt(11)
	v_add_u32_e32 v17, v17, v3
	s_waitcnt vmcnt(10)
	v_add_u32_e32 v17, v17, v4
	s_waitcnt vmcnt(9)
	v_add_u32_e32 v17, v17, v5
	s_waitcnt vmcnt(8)
	v_add_u32_e32 v17, v17, v6
	s_waitcnt vmcnt(7)
	v_add_u32_e32 v17, v17, v7
	s_waitcnt vmcnt(6)
	v_add_u32_e32 v17, v17, v8
	s_waitcnt vmcnt(5)
	v_add_u32_e32 v17, v17, v9
	s_waitcnt vmcnt(4)
	v_add_u32_e32 v17, v17, v10
	s_waitcnt vmcnt(3)
	v_add_u32_e32 v17, v17, v11
	s_waitcnt vmcnt(2)
	v_add_u32_e32 v17, v17, v12
	s_waitcnt vmcnt(1)
	v_add_u32_e32 v17, v17, v13
	s_waitcnt vmcnt(0)
	v_add_u32_e32 v17, v17, v14
	v_cmp_eq_u32_e32 vcc, s2, v17
	s_cbranch_vccnz .LBB0_3253
	s_and_b32 s7, s6, 0xff
	s_cmp_eq_u32 s7, 0
	s_mov_b64 s[46:47], -1
	s_cbranch_scc1 .LBB0_3258
	s_and_b64 vcc, exec, s[46:47]
	s_cbranch_vccz .LBB0_3253

.LBB0_3414:
	global_load_dword v15, v16, s[8:9] sc1
	s_waitcnt lgkmcnt(0)
	global_load_dword v0, v16, s[10:11] sc1
	global_load_dword v1, v16, s[12:13] sc1
	global_load_dword v2, v16, s[14:15] sc1
	global_load_dword v3, v16, s[16:17] sc1
	global_load_dword v4, v16, s[18:19] sc1
	global_load_dword v5, v16, s[20:21] sc1
	global_load_dword v6, v16, s[22:23] sc1
	global_load_dword v7, v16, s[24:25] sc1
	global_load_dword v8, v16, s[26:27] sc1
	global_load_dword v9, v16, s[28:29] sc1
	global_load_dword v10, v16, s[30:31] sc1
	global_load_dword v11, v16, s[34:35] sc1
	global_load_dword v12, v16, s[36:37] sc1
	global_load_dword v13, v16, s[38:39] sc1
	global_load_dword v14, v16, s[40:41] sc1
	s_mov_b64 s[42:43], -1
	s_mov_b64 s[4:5], -1
	s_waitcnt vmcnt(14)
	v_add_u32_e32 v17, v0, v15
	s_waitcnt vmcnt(13)
	v_add_u32_e32 v17, v17, v1
	s_waitcnt vmcnt(12)
	v_add_u32_e32 v17, v17, v2
	s_waitcnt vmcnt(11)
	v_add_u32_e32 v17, v17, v3
	s_waitcnt vmcnt(10)
	v_add_u32_e32 v17, v17, v4
	s_waitcnt vmcnt(9)
	v_add_u32_e32 v17, v17, v5
	s_waitcnt vmcnt(8)
	v_add_u32_e32 v17, v17, v6
	s_waitcnt vmcnt(7)
	v_add_u32_e32 v17, v17, v7
	s_waitcnt vmcnt(6)
	v_add_u32_e32 v17, v17, v8
	s_waitcnt vmcnt(5)
	v_add_u32_e32 v17, v17, v9
	s_waitcnt vmcnt(4)
	v_add_u32_e32 v17, v17, v10
	s_waitcnt vmcnt(3)
	v_add_u32_e32 v17, v17, v11
	s_waitcnt vmcnt(2)
	v_add_u32_e32 v17, v17, v12
	s_waitcnt vmcnt(1)
	v_add_u32_e32 v17, v17, v13
	s_waitcnt vmcnt(0)
	v_add_u32_e32 v17, v17, v14
	v_cmp_eq_u32_e32 vcc, s2, v17
	s_cbranch_vccnz .LBB0_3413
	s_and_b32 s42, s33, 0xff
	s_cmp_eq_u32 s42, 0
	s_mov_b64 s[42:43], -1
	s_mov_b64 s[44:45], -1
	s_cbranch_scc1 .LBB0_3418
	s_and_b64 vcc, exec, s[44:45]
	s_cbranch_vccz .LBB0_3413

.LBB0_3674:
	global_load_dword v15, v16, s[8:9] sc1
	global_load_dword v0, v16, s[10:11] sc1
	global_load_dword v1, v16, s[12:13] sc1
	global_load_dword v2, v16, s[14:15] sc1
	global_load_dword v3, v16, s[16:17] sc1
	global_load_dword v4, v16, s[18:19] sc1
	global_load_dword v5, v16, s[20:21] sc1
	global_load_dword v6, v16, s[22:23] sc1
	global_load_dword v7, v16, s[24:25] sc1
	global_load_dword v8, v16, s[26:27] sc1
	global_load_dword v9, v16, s[28:29] sc1
	global_load_dword v10, v16, s[30:31] sc1
	global_load_dword v11, v16, s[34:35] sc1
	global_load_dword v12, v16, s[36:37] sc1
	global_load_dword v13, v16, s[38:39] sc1
	global_load_dword v14, v16, s[40:41] sc1
	s_mov_b64 s[42:43], -1
	s_mov_b64 s[4:5], -1
	s_waitcnt vmcnt(14)
	v_add_u32_e32 v17, v0, v15
	s_waitcnt vmcnt(13)
	v_add_u32_e32 v17, v17, v1
	s_waitcnt vmcnt(12)
	v_add_u32_e32 v17, v17, v2
	s_waitcnt vmcnt(11)
	v_add_u32_e32 v17, v17, v3
	s_waitcnt vmcnt(10)
	v_add_u32_e32 v17, v17, v4
	s_waitcnt vmcnt(9)
	v_add_u32_e32 v17, v17, v5
	s_waitcnt vmcnt(8)
	v_add_u32_e32 v17, v17, v6
	s_waitcnt vmcnt(7)
	v_add_u32_e32 v17, v17, v7
	s_waitcnt vmcnt(6)
	v_add_u32_e32 v17, v17, v8
	s_waitcnt vmcnt(5)
	v_add_u32_e32 v17, v17, v9
	s_waitcnt vmcnt(4)
	v_add_u32_e32 v17, v17, v10
	s_waitcnt vmcnt(3)
	v_add_u32_e32 v17, v17, v11
	s_waitcnt vmcnt(2)
	v_add_u32_e32 v17, v17, v12
	s_waitcnt vmcnt(1)
	v_add_u32_e32 v17, v17, v13
	s_waitcnt vmcnt(0)
	v_add_u32_e32 v17, v17, v14
	v_cmp_eq_u32_e32 vcc, s33, v17
	s_cbranch_vccnz .LBB0_3673
	s_and_b32 s42, s2, 0xff
	s_cmp_eq_u32 s42, 0
	s_mov_b64 s[42:43], -1
	s_mov_b64 s[44:45], -1
	s_cbranch_scc1 .LBB0_3678
	s_and_b64 vcc, exec, s[44:45]
	s_cbranch_vccz .LBB0_3673

.LBB0_3754:
	global_load_dword v15, v16, s[6:7] sc1
	global_load_dword v0, v16, s[8:9] sc1
	global_load_dword v1, v16, s[10:11] sc1
	global_load_dword v2, v16, s[12:13] sc1
	global_load_dword v3, v16, s[14:15] sc1
	global_load_dword v4, v16, s[16:17] sc1
	global_load_dword v5, v16, s[18:19] sc1
	global_load_dword v6, v16, s[20:21] sc1
	global_load_dword v7, v16, s[22:23] sc1
	global_load_dword v8, v16, s[24:25] sc1
	global_load_dword v9, v16, s[26:27] sc1
	global_load_dword v10, v16, s[28:29] sc1
	global_load_dword v11, v16, s[30:31] sc1
	global_load_dword v12, v16, s[34:35] sc1
	global_load_dword v13, v16, s[36:37] sc1
	global_load_dword v14, v16, s[38:39] sc1
	s_mov_b64 s[40:41], -1
	s_mov_b64 s[4:5], -1
	s_waitcnt vmcnt(14)
	v_add_u32_e32 v17, v0, v15
	s_waitcnt vmcnt(13)
	v_add_u32_e32 v17, v17, v1
	s_waitcnt vmcnt(12)
	v_add_u32_e32 v17, v17, v2
	s_waitcnt vmcnt(11)
	v_add_u32_e32 v17, v17, v3
	s_waitcnt vmcnt(10)
	v_add_u32_e32 v17, v17, v4
	s_waitcnt vmcnt(9)
	v_add_u32_e32 v17, v17, v5
	s_waitcnt vmcnt(8)
	v_add_u32_e32 v17, v17, v6
	s_waitcnt vmcnt(7)
	v_add_u32_e32 v17, v17, v7
	s_waitcnt vmcnt(6)
	v_add_u32_e32 v17, v17, v8
	s_waitcnt vmcnt(5)
	v_add_u32_e32 v17, v17, v9
	s_waitcnt vmcnt(4)
	v_add_u32_e32 v17, v17, v10
	s_waitcnt vmcnt(3)
	v_add_u32_e32 v17, v17, v11
	s_waitcnt vmcnt(2)
	v_add_u32_e32 v17, v17, v12
	s_waitcnt vmcnt(1)
	v_add_u32_e32 v17, v17, v13
	s_waitcnt vmcnt(0)
	v_add_u32_e32 v17, v17, v14
	v_cmp_eq_u32_e32 vcc, s44, v17
	s_cbranch_vccnz .LBB0_3753
	s_and_b32 s40, s33, 0xff
	s_cmp_eq_u32 s40, 0
	s_mov_b64 s[40:41], -1
	s_mov_b64 s[42:43], -1
	s_cbranch_scc1 .LBB0_3758
	s_and_b64 vcc, exec, s[42:43]
	s_cbranch_vccz .LBB0_3753

.LBB0_3772:
	s_and_b32 s18, s22, 0xff
	s_mov_b64 s[4:5], -1
	s_cmp_lg_u32 s18, 0
	s_mov_b64 s[20:21], -1
	s_cbranch_scc0 .LBB0_3775
	s_and_b64 vcc, exec, s[20:21]
	s_cbranch_vccz .LBB0_3771

.LBB0_3789:
	s_and_b32 s4, s22, 0xff
	s_cmp_lg_u32 s4, 0
	s_mov_b64 s[18:19], -1
	s_cbranch_scc0 .LBB0_3792
	s_mov_b64 s[20:21], -1
	s_and_b64 vcc, exec, s[18:19]
	s_cbranch_vccz .LBB0_3788
